# attention band K/V staging: the four serialized V-row loads (load, vmcnt(0), 8 ds_write each) issued together with the K loads and consumed with counted waits
# baseline (speedup 1.0000x reference)
; __device__ __forceinline__ void attn_unit(const Ptrs& P, int l, int b, int gk, int n, unsigned char* lds, int tid, bool dost) {
;     ...
;         const int key = tid >> 1, half = tid & 1; const bool valid = (n >= 2) || (n == 1 && key >= 128);
;         u32x4 kv[4], vv[4];
;         if (valid) { const bf16_t* rp = PJ + (size_t)(b * SEQ + (n - 2) * 128 + key) * PW + gk * 64 + half * 32;
; #pragma unroll
;             for (int i = 0; i < 4; ++i) { kv[i] = *(const u32x4*)(rp + C_AK + 8 * i); vv[i] = *(const u32x4*)(rp + C_AV + 8 * i); } }
;         else {
; #pragma unroll
;             for (int i = 0; i < 4; ++i) { kv[i] = (u32x4){0u, 0u, 0u, 0u}; vv[i] = (u32x4){0u, 0u, 0u, 0u}; } }
; #pragma unroll
;         for (int i = 0; i < 4; ++i) {
;             *(u32x4*)(lds + AT_KS + key * 144 + half * 64 + i * 16) = kv[i];
;             const int d0 = half * 32 + i * 8;
;             Vt[(d0 + 0) * 280 + key] = (bf16_t)(vv[i].x & 0xffffu); Vt[(d0 + 1) * 280 + key] = (bf16_t)(vv[i].x >> 16);
;             Vt[(d0 + 2) * 280 + key] = (bf16_t)(vv[i].y & 0xffffu); Vt[(d0 + 3) * 280 + key] = (bf16_t)(vv[i].y >> 16);
;             Vt[(d0 + 4) * 280 + key] = (bf16_t)(vv[i].z & 0xffffu); Vt[(d0 + 5) * 280 + key] = (bf16_t)(vv[i].z >> 16);
;             Vt[(d0 + 6) * 280 + key] = (bf16_t)(vv[i].w & 0xffffu); Vt[(d0 + 7) * 280 + key] = (bf16_t)(vv[i].w >> 16);
;         }
;     }
;     if (tid < 32) {
;         const int m = tid >> 1, half = tid & 1; const bf16_t* rp = PJ + (size_t)(MMAIN + b * NMETA + m) * PW + gk * 64 + half * 32;
; #pragma unroll
;         for (int i = 0; i < 4; ++i) { const u32x4 kvv = *(const u32x4*)(rp + C_AK + 8 * i); const u32x4 vvv = *(const u32x4*)(rp + C_AV + 8 * i);
;             *(u32x4*)(lds + AT_KM + m * 144 + half * 64 + i * 16) = kvv;
;             const int d0 = half * 32 + i * 8;
;             Vt[(d0 + 0) * 280 + 256 + m] = (bf16_t)(vvv.x & 0xffffu); Vt[(d0 + 1) * 280 + 256 + m] = (bf16_t)(vvv.x >> 16);
;             Vt[(d0 + 2) * 280 + 256 + m] = (bf16_t)(vvv.y & 0xffffu); Vt[(d0 + 3) * 280 + 256 + m] = (bf16_t)(vvv.y >> 16);
;             Vt[(d0 + 4) * 280 + 256 + m] = (bf16_t)(vvv.z & 0xffffu); Vt[(d0 + 5) * 280 + 256 + m] = (bf16_t)(vvv.z >> 16);
;             Vt[(d0 + 6) * 280 + 256 + m] = (bf16_t)(vvv.w & 0xffffu); Vt[(d0 + 7) * 280 + 256 + m] = (bf16_t)(vvv.w >> 16); }
;     }
.LBB0_313:
	s_or_b64 exec, exec, s[4:5]
	s_movk_i32 s4, 0x90
	v_mul_lo_u32 v47, v49, s4
	v_add_u32_e32 v17, 0, v47
	v_add_u32_e32 v50, v17, v46
	s_movk_i32 s4, 0xff72
	s_waitcnt vmcnt(7)
	ds_write_b128 v50, v[34:37]
	v_mul_i32_i24_e32 v34, 0x118, v48
	v_mul_lo_u32 v51, v49, s4
	v_lshlrev_b32_e32 v34, 1, v34
	v_add3_u32 v35, v17, v51, v34
	v_lshlrev_b32_e32 v17, 1, v49
	v_add3_u32 v17, 0, v34, v17
	v_cmp_gt_i32_e32 vcc, 32, v98
	s_waitcnt vmcnt(3)
	ds_write_b16 v35, v42 offset:36864
	ds_write_b16_d16_hi v17, v42 offset:37424
	ds_write_b16 v17, v43 offset:37984
	ds_write_b16_d16_hi v17, v43 offset:38544
	ds_write_b16 v17, v44 offset:39104
	ds_write_b16_d16_hi v17, v44 offset:39664
	ds_write_b16 v17, v45 offset:40224
	ds_write_b16_d16_hi v17, v45 offset:40784
	ds_write_b128 v50, v[26:29] offset:16
	s_waitcnt vmcnt(2)
	ds_write_b16 v35, v38 offset:41344
	ds_write_b16_d16_hi v17, v38 offset:41904
	ds_write_b16 v17, v39 offset:42464
	ds_write_b16_d16_hi v17, v39 offset:43024
	ds_write_b16 v17, v40 offset:43584
	ds_write_b16_d16_hi v17, v40 offset:44144
	ds_write_b16 v17, v41 offset:44704
	ds_write_b16_d16_hi v17, v41 offset:45264
	ds_write_b128 v50, v[22:25] offset:32
	s_waitcnt vmcnt(1)
	ds_write_b16 v35, v30 offset:45824
	ds_write_b16_d16_hi v17, v30 offset:46384
	ds_write_b16 v17, v31 offset:46944
	ds_write_b16_d16_hi v17, v31 offset:47504
	ds_write_b16 v17, v32 offset:48064
	ds_write_b16_d16_hi v17, v32 offset:48624
	ds_write_b16 v17, v33 offset:49184
	ds_write_b16_d16_hi v17, v33 offset:49744
	ds_write_b128 v50, v[10:13] offset:48
	s_waitcnt vmcnt(0)
	ds_write_b16 v35, v18 offset:50304
	ds_write_b16_d16_hi v17, v18 offset:50864
	ds_write_b16 v17, v19 offset:51424
	ds_write_b16_d16_hi v17, v19 offset:51984
	ds_write_b16 v17, v20 offset:52544
	ds_write_b16_d16_hi v17, v20 offset:53104
	ds_write_b16 v17, v21 offset:53664
	ds_write_b16_d16_hi v17, v21 offset:54224
	s_and_saveexec_b64 s[4:5], vcc
	s_cbranch_execz .LBB0_315
	v_lshl_add_u32 v10, s8, 4, v49
	v_add_u32_e32 v10, 0x8000, v10
	v_mad_i64_i32 v[10:11], s[6:7], v10, s34, v[86:87]
	s_lshl_b32 s96, s9, 7
	v_lshl_add_u64 v[10:11], v[10:11], 0, s[96:97]
	v_mov_b32_e32 v49, v16
	v_lshl_add_u64 v[10:11], v[48:49], 1, v[10:11]
	s_mov_b64 s[6:7], 0x1800
	v_add_co_u32_e32 v30, vcc, 0x1000, v10
	v_lshl_add_u64 v[26:27], v[10:11], 0, s[6:7]
	s_nop 0
	v_addc_co_u32_e32 v31, vcc, 0, v11, vcc
	global_load_dwordx4 v[52:55], v[30:31], off offset:2048
	global_load_dwordx4 v[56:59], v[26:27], off offset:48
	global_load_dwordx4 v[60:63], v[26:27], off offset:32
	global_load_dwordx4 v[64:67], v[26:27], off offset:16
	global_load_dwordx4 v[68:71], v[30:31], off offset:2304
	global_load_dwordx4 v[72:75], v[30:31], off offset:2320
	global_load_dwordx4 v[76:79], v[30:31], off offset:2336
	global_load_dwordx4 v[80:83], v[30:31], off offset:2352
	s_nop 0
	s_nop 0
	s_nop 0
	s_nop 0
	v_readlane_b32 s6, v255, 23
	s_nop 1
	v_add3_u32 v32, s6, v47, v46
	s_waitcnt vmcnt(7)
	ds_write_b128 v32, v[52:55]
	s_nop 0
	s_waitcnt vmcnt(3)
	ds_write_b16 v17, v68 offset:37376
	ds_write_b16_d16_hi v17, v68 offset:37936
	ds_write_b16 v17, v69 offset:38496
	ds_write_b16_d16_hi v17, v69 offset:39056
	ds_write_b16 v17, v70 offset:39616
	ds_write_b16_d16_hi v17, v70 offset:40176
	ds_write_b16 v17, v71 offset:40736
	ds_write_b16_d16_hi v17, v71 offset:41296
	ds_write_b128 v32, v[64:67] offset:16
	s_nop 0
	s_waitcnt vmcnt(2)
	ds_write_b16 v17, v72 offset:41856
	ds_write_b16_d16_hi v17, v72 offset:42416
	ds_write_b16 v17, v73 offset:42976
	ds_write_b16_d16_hi v17, v73 offset:43536
	ds_write_b16 v17, v74 offset:44096
	ds_write_b16_d16_hi v17, v74 offset:44656
	ds_write_b16 v17, v75 offset:45216
	ds_write_b16_d16_hi v17, v75 offset:45776
	ds_write_b128 v32, v[60:63] offset:32
	s_nop 0
	s_waitcnt vmcnt(1)
	ds_write_b16 v17, v76 offset:46336
	ds_write_b16_d16_hi v17, v76 offset:46896
	ds_write_b16 v17, v77 offset:47456
	ds_write_b16_d16_hi v17, v77 offset:48016
	ds_write_b16 v17, v78 offset:48576
	ds_write_b16_d16_hi v17, v78 offset:49136
	ds_write_b16 v17, v79 offset:49696
	ds_write_b16_d16_hi v17, v79 offset:50256
	ds_write_b128 v32, v[56:59] offset:48
	s_nop 0
	s_waitcnt vmcnt(0)
	ds_write_b16 v17, v80 offset:50816
	ds_write_b16_d16_hi v17, v80 offset:51376
	ds_write_b16 v17, v81 offset:51936
	ds_write_b16_d16_hi v17, v81 offset:52496
	ds_write_b16 v17, v82 offset:53056
	ds_write_b16_d16_hi v17, v82 offset:53616
	ds_write_b16 v17, v83 offset:54176
	ds_write_b16_d16_hi v17, v83 offset:54736
